# select: wait for stale key-tile loads before (not after) issuing the next item's query loads, so they fly under the searches
# speedup vs baseline: 1.0612x; 1.0012x over previous
.LBB0_121:
	s_or_b64 exec, exec, s[4:5]
	s_cmp_lg_u32 s10, 1
	s_waitcnt vmcnt(0) lgkmcnt(0)
	s_barrier
	s_cbranch_scc1 .LBB0_123
	global_load_dwordx4 v[30:33], v[82:83], off
	global_load_dwordx4 v[22:25], v[82:83], off offset:64
	global_load_dwordx4 v[18:21], v[82:83], off offset:128
	global_load_dwordx4 v[14:17], v[82:83], off offset:192
	global_load_dwordx4 v[10:13], v[82:83], off offset:256
	global_load_dwordx4 v[6:9], v[82:83], off offset:320
	global_load_dwordx4 v[2:5], v[82:83], off offset:384
	global_load_dwordx4 v[26:29], v[82:83], off offset:448
	global_load_dwordx2 v[70:71], v[84:85], off
.LBB0_123:
	v_sub_u32_e32 v34, s75, v172
	v_lshlrev_b32_e64 v35, v34, 2
	v_cmp_gt_i32_e32 vcc, 0, v34
	v_add_u32_e32 v35, -1, v35
	v_cmp_gt_i32_e64 s[4:5], 31, v34
	v_cndmask_b32_e64 v35, v35, 0, vcc
	v_add_u32_e32 v48, s9, v0
	v_cndmask_b32_e64 v46, -1, v35, s[4:5]
	v_lshlrev_b32_e64 v35, v34, 4
	v_add_u32_e32 v35, -1, v35
	v_cndmask_b32_e64 v35, v35, 0, vcc
	v_cmp_gt_i32_e32 vcc, 30, v34
	v_bfe_i32 v58, v46, 0, 1
	s_nop 0
	v_cndmask_b32_e32 v47, -1, v35, vcc
	ds_read_b128 v[50:53], v48
	ds_read_b128 v[42:45], v48 offset:16
	ds_read_b128 v[38:41], v48 offset:32
	ds_read_b128 v[34:37], v48 offset:48
	ds_read_b128 v[54:57], v48 offset:9248
	s_waitcnt lgkmcnt(4)
	v_ashrrev_i32_e32 v49, 31, v50
	v_or_b32_e32 v49, 0x80000000, v49
	v_bitop3_b32 v138, v58, v49, v50 bitop3:0x60
	v_bfe_i32 v50, v47, 0, 1
	s_waitcnt lgkmcnt(0)
	v_ashrrev_i32_e32 v49, 31, v54
	v_or_b32_e32 v49, 0x80000000, v49
	v_bitop3_b32 v98, v50, v49, v54 bitop3:0x60
	v_ashrrev_i32_e32 v49, 31, v51
	v_or_b32_e32 v49, 0x80000000, v49
	v_bfe_i32 v50, v46, 1, 1
	v_bitop3_b32 v140, v50, v49, v51 bitop3:0x60
	v_ashrrev_i32_e32 v51, 31, v52
	v_or_b32_e32 v51, 0x80000000, v51
	v_bfe_i32 v54, v46, 2, 1
	v_bitop3_b32 v139, v54, v51, v52 bitop3:0x60
	v_ashrrev_i32_e32 v51, 31, v56
	v_or_b32_e32 v51, 0x80000000, v51
	v_bfe_i32 v52, v47, 2, 1
	v_bitop3_b32 v99, v52, v51, v56 bitop3:0x60
	v_ashrrev_i32_e32 v51, 31, v53
	v_ashrrev_i32_e32 v49, 31, v55
	v_or_b32_e32 v51, 0x80000000, v51
	v_bfe_i32 v52, v46, 3, 1
	v_or_b32_e32 v49, 0x80000000, v49
	v_bfe_i32 v50, v47, 1, 1
	v_bitop3_b32 v141, v52, v51, v53 bitop3:0x60
	v_ashrrev_i32_e32 v51, 31, v57
	v_bitop3_b32 v107, v50, v49, v55 bitop3:0x60
	v_or_b32_e32 v51, 0x80000000, v51
	v_bfe_i32 v52, v47, 3, 1
	v_max_u32_e32 v50, v98, v107
	v_bitop3_b32 v108, v52, v51, v57 bitop3:0x60
	v_max3_u32 v54, v50, v99, v108
	ds_read_b128 v[50:53], v48 offset:9264
	v_ashrrev_i32_e32 v55, 31, v42
	v_or_b32_e32 v55, 0x80000000, v55
	v_bfe_i32 v56, v46, 4, 1
	v_bitop3_b32 v142, v56, v55, v42 bitop3:0x60
	s_waitcnt lgkmcnt(0)
	v_ashrrev_i32_e32 v42, 31, v50
	v_or_b32_e32 v42, 0x80000000, v42
	v_bfe_i32 v55, v47, 4, 1
	v_bitop3_b32 v109, v55, v42, v50 bitop3:0x60
	v_ashrrev_i32_e32 v42, 31, v43
	v_or_b32_e32 v42, 0x80000000, v42
	v_bfe_i32 v50, v46, 5, 1
	v_max_u32_e32 v49, v138, v140
	v_bitop3_b32 v146, v50, v42, v43 bitop3:0x60
	v_ashrrev_i32_e32 v42, 31, v51
	v_max3_u32 v49, v49, v139, v141
	v_or_b32_e32 v42, 0x80000000, v42
	v_bfe_i32 v43, v47, 5, 1
	v_bitop3_b32 v113, v43, v42, v51 bitop3:0x60
	v_max3_u32 v42, v49, v142, v146
	v_ashrrev_i32_e32 v49, 31, v44
	v_or_b32_e32 v49, 0x80000000, v49
	v_bfe_i32 v50, v46, 6, 1
	v_bitop3_b32 v143, v50, v49, v44 bitop3:0x60
	v_ashrrev_i32_e32 v44, 31, v52
	v_or_b32_e32 v44, 0x80000000, v44
	v_bfe_i32 v49, v47, 6, 1
	v_bitop3_b32 v110, v49, v44, v52 bitop3:0x60
	v_ashrrev_i32_e32 v44, 31, v45
	v_or_b32_e32 v44, 0x80000000, v44
	v_bfe_i32 v49, v46, 7, 1
	v_bitop3_b32 v147, v49, v44, v45 bitop3:0x60
	v_ashrrev_i32_e32 v44, 31, v53
	v_or_b32_e32 v44, 0x80000000, v44
	v_bfe_i32 v45, v47, 7, 1
	v_max3_u32 v43, v54, v109, v113
	v_bitop3_b32 v114, v45, v44, v53 bitop3:0x60
	v_max3_u32 v49, v42, v143, v147
	v_max3_u32 v50, v43, v110, v114
	ds_read_b128 v[42:45], v48 offset:9280
	v_ashrrev_i32_e32 v51, 31, v38
	v_or_b32_e32 v51, 0x80000000, v51
	v_bfe_i32 v52, v46, 8, 1
	v_bitop3_b32 v144, v52, v51, v38 bitop3:0x60
	s_waitcnt lgkmcnt(0)
	v_ashrrev_i32_e32 v38, 31, v42
	v_or_b32_e32 v38, 0x80000000, v38
	v_bfe_i32 v51, v47, 8, 1
	v_bitop3_b32 v111, v51, v38, v42 bitop3:0x60
	v_ashrrev_i32_e32 v38, 31, v39
	v_or_b32_e32 v38, 0x80000000, v38
	v_bfe_i32 v42, v46, 9, 1
	v_bitop3_b32 v148, v42, v38, v39 bitop3:0x60
	v_ashrrev_i32_e32 v38, 31, v43
	v_or_b32_e32 v38, 0x80000000, v38
	v_bfe_i32 v39, v47, 9, 1
	v_ashrrev_i32_e32 v42, 31, v40
	v_bitop3_b32 v115, v39, v38, v43 bitop3:0x60
	v_or_b32_e32 v42, 0x80000000, v42
	v_bfe_i32 v43, v46, 10, 1
	v_bitop3_b32 v145, v43, v42, v40 bitop3:0x60
	v_ashrrev_i32_e32 v40, 31, v44
	v_or_b32_e32 v40, 0x80000000, v40
	v_bfe_i32 v42, v47, 10, 1
	v_bitop3_b32 v112, v42, v40, v44 bitop3:0x60
	v_ashrrev_i32_e32 v40, 31, v41
	v_or_b32_e32 v40, 0x80000000, v40
	v_bfe_i32 v42, v46, 11, 1
	v_bitop3_b32 v149, v42, v40, v41 bitop3:0x60
	v_ashrrev_i32_e32 v40, 31, v45
	v_or_b32_e32 v40, 0x80000000, v40
	v_bfe_i32 v41, v47, 11, 1
	v_max3_u32 v38, v49, v144, v148
	v_max3_u32 v39, v50, v111, v115
	v_bitop3_b32 v116, v41, v40, v45 bitop3:0x60
	v_max3_u32 v42, v38, v145, v149
	v_max3_u32 v43, v39, v112, v116
	ds_read_b128 v[38:41], v48 offset:9296
	v_ashrrev_i32_e32 v44, 31, v34
	v_or_b32_e32 v44, 0x80000000, v44
	v_bfe_i32 v45, v46, 12, 1
	v_bitop3_b32 v150, v45, v44, v34 bitop3:0x60
	s_waitcnt lgkmcnt(0)
	v_ashrrev_i32_e32 v34, 31, v38
	v_or_b32_e32 v34, 0x80000000, v34
	v_bfe_i32 v44, v47, 12, 1
	v_bitop3_b32 v117, v44, v34, v38 bitop3:0x60
	v_ashrrev_i32_e32 v34, 31, v35
	v_or_b32_e32 v34, 0x80000000, v34
	v_bfe_i32 v38, v46, 13, 1
	v_bitop3_b32 v152, v38, v34, v35 bitop3:0x60
	v_ashrrev_i32_e32 v34, 31, v39
	v_or_b32_e32 v34, 0x80000000, v34
	v_bfe_i32 v35, v47, 13, 1
	v_ashrrev_i32_e32 v38, 31, v36
	v_bitop3_b32 v119, v35, v34, v39 bitop3:0x60
	v_or_b32_e32 v38, 0x80000000, v38
	v_bfe_i32 v39, v46, 14, 1
	v_bitop3_b32 v151, v39, v38, v36 bitop3:0x60
	v_ashrrev_i32_e32 v36, 31, v40
	v_or_b32_e32 v36, 0x80000000, v36
	v_bfe_i32 v38, v47, 14, 1
	v_bitop3_b32 v118, v38, v36, v40 bitop3:0x60
	v_ashrrev_i32_e32 v36, 31, v37
	v_or_b32_e32 v36, 0x80000000, v36
	v_bfe_i32 v38, v46, 15, 1
	v_bitop3_b32 v154, v38, v36, v37 bitop3:0x60
	v_ashrrev_i32_e32 v36, 31, v41
	v_or_b32_e32 v36, 0x80000000, v36
	v_bfe_i32 v37, v47, 15, 1
	v_max3_u32 v34, v42, v150, v152
	v_max3_u32 v35, v43, v117, v119
	v_bitop3_b32 v121, v37, v36, v41 bitop3:0x60
	v_max3_u32 v42, v34, v151, v154
	v_max3_u32 v43, v35, v118, v121
	ds_read_b128 v[34:37], v48 offset:64
	ds_read_b128 v[38:41], v48 offset:9312
	v_bfe_i32 v45, v46, 16, 1
	s_waitcnt lgkmcnt(1)
	v_ashrrev_i32_e32 v44, 31, v34
	v_or_b32_e32 v44, 0x80000000, v44
	v_bitop3_b32 v153, v45, v44, v34 bitop3:0x60
	s_waitcnt lgkmcnt(0)
	v_ashrrev_i32_e32 v34, 31, v38
	v_or_b32_e32 v34, 0x80000000, v34
	v_bfe_i32 v44, v47, 16, 1
	v_bitop3_b32 v120, v44, v34, v38 bitop3:0x60
	v_ashrrev_i32_e32 v34, 31, v35
	v_or_b32_e32 v34, 0x80000000, v34
	v_bfe_i32 v38, v46, 17, 1
	v_bitop3_b32 v156, v38, v34, v35 bitop3:0x60
	v_ashrrev_i32_e32 v34, 31, v39
	v_or_b32_e32 v34, 0x80000000, v34
	v_bfe_i32 v35, v47, 17, 1
	v_ashrrev_i32_e32 v38, 31, v36
	v_bitop3_b32 v123, v35, v34, v39 bitop3:0x60
	v_or_b32_e32 v38, 0x80000000, v38
	v_bfe_i32 v39, v46, 18, 1
	v_bitop3_b32 v155, v39, v38, v36 bitop3:0x60
	v_ashrrev_i32_e32 v36, 31, v40
	v_or_b32_e32 v36, 0x80000000, v36
	v_bfe_i32 v38, v47, 18, 1
	v_bitop3_b32 v122, v38, v36, v40 bitop3:0x60
	v_ashrrev_i32_e32 v36, 31, v37
	v_or_b32_e32 v36, 0x80000000, v36
	v_bfe_i32 v38, v46, 19, 1
	v_bitop3_b32 v157, v38, v36, v37 bitop3:0x60
	v_ashrrev_i32_e32 v36, 31, v41
	v_or_b32_e32 v36, 0x80000000, v36
	v_bfe_i32 v37, v47, 19, 1
	v_max3_u32 v34, v42, v153, v156
	v_max3_u32 v35, v43, v120, v123
	v_bitop3_b32 v124, v37, v36, v41 bitop3:0x60
	v_max3_u32 v42, v34, v155, v157
	v_max3_u32 v43, v35, v122, v124
	ds_read_b128 v[34:37], v48 offset:80
	ds_read_b128 v[38:41], v48 offset:9328
	v_bfe_i32 v45, v46, 20, 1
	s_waitcnt lgkmcnt(1)
	v_ashrrev_i32_e32 v44, 31, v34
	v_or_b32_e32 v44, 0x80000000, v44
	v_bitop3_b32 v158, v45, v44, v34 bitop3:0x60
	s_waitcnt lgkmcnt(0)
	v_ashrrev_i32_e32 v34, 31, v38
	v_or_b32_e32 v34, 0x80000000, v34
	v_bfe_i32 v44, v47, 20, 1
	v_bitop3_b32 v125, v44, v34, v38 bitop3:0x60
	v_ashrrev_i32_e32 v34, 31, v35
	v_or_b32_e32 v34, 0x80000000, v34
	v_bfe_i32 v38, v46, 21, 1
	v_bitop3_b32 v160, v38, v34, v35 bitop3:0x60
	v_ashrrev_i32_e32 v34, 31, v39
	v_or_b32_e32 v34, 0x80000000, v34
	v_bfe_i32 v35, v47, 21, 1
	v_ashrrev_i32_e32 v38, 31, v36
	v_bitop3_b32 v127, v35, v34, v39 bitop3:0x60
	v_or_b32_e32 v38, 0x80000000, v38
	v_bfe_i32 v39, v46, 22, 1
	v_bitop3_b32 v159, v39, v38, v36 bitop3:0x60
	v_ashrrev_i32_e32 v36, 31, v40
	v_or_b32_e32 v36, 0x80000000, v36
	v_bfe_i32 v38, v47, 22, 1
	v_bitop3_b32 v126, v38, v36, v40 bitop3:0x60
	v_ashrrev_i32_e32 v36, 31, v37
	v_or_b32_e32 v36, 0x80000000, v36
	v_bfe_i32 v38, v46, 23, 1
	v_bitop3_b32 v161, v38, v36, v37 bitop3:0x60
	v_ashrrev_i32_e32 v36, 31, v41
	v_or_b32_e32 v36, 0x80000000, v36
	v_bfe_i32 v37, v47, 23, 1
	v_max3_u32 v34, v42, v158, v160
	v_max3_u32 v35, v43, v125, v127
	v_bitop3_b32 v128, v37, v36, v41 bitop3:0x60
	v_max3_u32 v42, v34, v159, v161
	v_max3_u32 v43, v35, v126, v128
	ds_read_b128 v[34:37], v48 offset:96
	ds_read_b128 v[38:41], v48 offset:9344
	v_bfe_i32 v45, v46, 24, 1
	s_waitcnt lgkmcnt(1)
	v_ashrrev_i32_e32 v44, 31, v34
	v_or_b32_e32 v44, 0x80000000, v44
	v_bitop3_b32 v167, v45, v44, v34 bitop3:0x60
	s_waitcnt lgkmcnt(0)
	v_ashrrev_i32_e32 v34, 31, v38
	v_or_b32_e32 v34, 0x80000000, v34
	v_bfe_i32 v44, v47, 24, 1
	v_bitop3_b32 v129, v44, v34, v38 bitop3:0x60
	v_ashrrev_i32_e32 v34, 31, v35
	v_or_b32_e32 v34, 0x80000000, v34
	v_bfe_i32 v38, v46, 25, 1
	v_bitop3_b32 v169, v38, v34, v35 bitop3:0x60
	v_ashrrev_i32_e32 v34, 31, v39
	v_or_b32_e32 v34, 0x80000000, v34
	v_bfe_i32 v35, v47, 25, 1
	v_ashrrev_i32_e32 v38, 31, v36
	v_bitop3_b32 v131, v35, v34, v39 bitop3:0x60
	v_or_b32_e32 v38, 0x80000000, v38
	v_bfe_i32 v39, v46, 26, 1
	v_bitop3_b32 v168, v39, v38, v36 bitop3:0x60
	v_ashrrev_i32_e32 v36, 31, v40
	v_or_b32_e32 v36, 0x80000000, v36
	v_bfe_i32 v38, v47, 26, 1
	v_bitop3_b32 v130, v38, v36, v40 bitop3:0x60
	v_ashrrev_i32_e32 v36, 31, v37
	v_or_b32_e32 v36, 0x80000000, v36
	v_bfe_i32 v38, v46, 27, 1
	v_bitop3_b32 v170, v38, v36, v37 bitop3:0x60
	v_ashrrev_i32_e32 v36, 31, v41
	v_or_b32_e32 v36, 0x80000000, v36
	v_bfe_i32 v37, v47, 27, 1
	v_max3_u32 v34, v42, v167, v169
	v_max3_u32 v35, v43, v129, v131
	v_bitop3_b32 v132, v37, v36, v41 bitop3:0x60
	v_max3_u32 v42, v34, v168, v170
	v_max3_u32 v43, v35, v130, v132
	ds_read_b128 v[34:37], v48 offset:112
	ds_read_b128 v[38:41], v48 offset:9360
	v_bfe_i32 v45, v46, 28, 1
	s_waitcnt lgkmcnt(0)
	s_waitcnt lgkmcnt(0)
	v_ashrrev_i32_e32 v44, 31, v34
	v_or_b32_e32 v44, 0x80000000, v44
	v_bitop3_b32 v173, v45, v44, v34 bitop3:0x60
	v_ashrrev_i32_e32 v34, 31, v38
	v_or_b32_e32 v34, 0x80000000, v34
	v_bfe_i32 v44, v47, 28, 1
	v_bitop3_b32 v133, v44, v34, v38 bitop3:0x60
	v_ashrrev_i32_e32 v34, 31, v35
	v_or_b32_e32 v34, 0x80000000, v34
	v_bfe_i32 v38, v46, 29, 1
	v_bitop3_b32 v174, v38, v34, v35 bitop3:0x60
	v_ashrrev_i32_e32 v34, 31, v39
	v_or_b32_e32 v34, 0x80000000, v34
	v_bfe_i32 v35, v47, 29, 1
	v_ashrrev_i32_e32 v38, 31, v36
	v_bitop3_b32 v134, v35, v34, v39 bitop3:0x60
	v_or_b32_e32 v38, 0x80000000, v38
	v_bfe_i32 v39, v46, 30, 1
	v_bitop3_b32 v175, v39, v38, v36 bitop3:0x60
	v_ashrrev_i32_e32 v36, 31, v40
	v_or_b32_e32 v36, 0x80000000, v36
	v_bfe_i32 v38, v47, 30, 1
	v_bitop3_b32 v136, v38, v36, v40 bitop3:0x60
	v_ashrrev_i32_e32 v36, 31, v37
	v_or_b32_e32 v36, 0x80000000, v36
	v_ashrrev_i32_e32 v38, 31, v46
	v_bitop3_b32 v176, v38, v36, v37 bitop3:0x60
	v_ashrrev_i32_e32 v36, 31, v41
	v_or_b32_e32 v36, 0x80000000, v36
	v_ashrrev_i32_e32 v37, 31, v47
	v_max3_u32 v34, v42, v173, v174
	v_max3_u32 v35, v43, v133, v134
	v_bitop3_b32 v137, v37, v36, v41 bitop3:0x60
	v_max3_u32 v185, v34, v175, v176
	v_max3_u32 v177, v35, v136, v137
	s_barrier
	s_cmp_lt_i32 s10, 2
	v_mov_b32_e32 v46, 0
	s_cbranch_scc1 .LBB0_129
